# M1: the two gate waves are waves 0 and 5 (different SIMDs) instead of 0 and 4 (same SIMD), so their VALU-heavy gate sections do not share one VALU
# baseline (speedup 1.0000x reference)
; __device__ __forceinline__ float log_sigmoid_f(float x) { return fminf(x, 0.f) - log1pf(expf(-fabsf(x))); }
; __device__ __forceinline__ void m1_phase(const Params& p, unsigned char* ldsg, int G) {
;     const int tid = threadIdx.x, lane = tid & 63, wave = __builtin_amdgcn_readfirstlane(tid >> 6), fr = lane & 15, fq = lane >> 4;
;     const int half = wave >> 2, hw = wave & 3, htid = tid & 255;
;     unsigned char* ws = p.ws;
;     const bf16* PROJ = (const bf16*)(ws + WS_HB); const float* GATES = (const float*)(ws + WS_GATES);
;     bf16* DCB = (bf16*)p.out; bf16* QKC = (bf16*)((unsigned char*)p.out + 32 * MiB); float* DN = (float*)(ws + WS_DN); float* GARR = (float*)(ws + WS_SC); float* AMAXARR = GARR + 1024;
;     bf16* KT = (bf16*)(ldsg + half * 40960); bf16* VT = KT + 128 * TP; float* sW = (float*)(ldsg + half * 40960 + 36864);
;     for (int r = blockIdx.x; r < NCH * NH / 2; r += G) {
;         const int c = r >> 1, h = 2 * (r & 1) + half, u = c * 4 + h, t0 = c * CL;
;         if (hw == 0) {
;             const float ig = GATES[(size_t)(t0 + lane) * 8 + h], fp = GATES[(size_t)(t0 + lane) * 8 + 4 + h];
;             const float b = wave_incl_sum(log_sigmoid_f(fp), lane);
;             const float g = __shfl(b, 63);
;             const float a = g - b + ig;
;             const float amax = wave_max(a);
;             sW[lane] = expf(a - amax);
;             if (lane == 0) { GARR[h * NCH + c] = g; AMAXARR[h * NCH + c] = amax; }
;         }
;         const int rg = htid >> 4, cgp = htid & 15, l0 = 4 * rg;
.LBB0_608:
	s_or_b64 exec, exec, s[0:1]
	s_add_u32 s56, s70, 0x2000000
	s_addc_u32 s57, s71, 0
	s_add_u32 s34, s72, 0x500000
	s_addc_u32 s35, s73, 0
	s_add_u32 s36, s72, 0x501000
	v_lshrrev_b32_e32 v159, 4, v153
	s_addc_u32 s37, s73, 0
	v_readfirstlane_b32 s0, v240
	s_cmpk_gt_i32 s86, 0x1ff
	v_cmp_gt_u32_e64 s[8:9], 2, v153
	v_cmp_gt_u32_e64 s[10:11], 4, v153
	v_cmp_gt_u32_e64 s[12:13], 8, v153
	v_cmp_gt_u32_e64 s[14:15], 32, v153
	v_lshlrev_b32_e32 v92, 3, v159
	v_lshlrev_b32_e32 v167, 8, v152
	v_and_b32_e32 v157, 8, v152
	s_waitcnt lgkmcnt(0)
	s_barrier
	s_cbranch_scc1 .LBB0_648
	s_ashr_i32 s2, s0, 2
	v_and_b32_e32 v64, 0x78, v230
	s_mul_i32 s1, s2, 0xa000
	v_mov_b32_e32 v67, 0
	v_lshlrev_b32_e32 v66, 1, v64
	v_and_b32_e32 v0, 56, v230
	s_add_i32 s1, s1, 0
	v_and_b32_e32 v2, 0xff, v152
	v_lshl_add_u64 v[68:69], s[56:57], 0, v[66:67]
	v_bitop3_b32 v0, v175, v0, 60 bitop3:0x6c
	v_and_b32_e32 v66, 0x100, v167
	s_and_b32 s3, s0, 3
	v_and_b32_e32 v118, 60, v175
	v_lshl_add_u32 v4, v0, 1, s1
	v_lshl_add_u64 v[0:1], s[70:71], 0, v[66:67]
	v_mov_b32_e32 v93, v67
	s_movk_i32 s0, 0x80
	v_lshlrev_b32_e32 v66, 2, v2
	v_mov_b32_e32 v3, s1
	v_lshl_add_u32 v65, v153, 2, s1
	v_lshl_add_u32 v120, v118, 2, s1
	v_lshl_or_b32 v5, s3, 5, v234
	v_lshl_add_u64 v[70:71], v[0:1], 0, v[92:93]
	v_cmp_gt_u32_e64 s[20:21], s0, v2
	s_movk_i32 s6, 0x90
	v_lshl_add_u64 v[0:1], s[72:73], 0, v[66:67]
	s_mov_b64 s[0:1], 0x480000
	v_mad_u32_u24 v93, v2, s6, v3
	v_lshl_add_u64 v[72:73], v[0:1], 0, s[0:1]
	v_mad_u32_u24 v1, v5, s6, v3
	v_bitop3_b32 v2, v5, v92, 40 bitop3:0x6c
	v_lshl_add_u32 v121, v2, 1, v1
	v_or_b32_e32 v2, 32, v92
	v_bitop3_b32 v7, v5, v2, 40 bitop3:0x6c
	v_or_b32_e32 v5, 16, v5
	v_lshl_add_u32 v122, v7, 1, v1
	v_add_u32_e32 v1, 0x900, v1
	v_bitop3_b32 v7, v5, v92, 56 bitop3:0x6c
	v_bitop3_b32 v2, v5, v2, 56 bitop3:0x6c
	v_lshl_add_u32 v123, v7, 1, v1
	v_lshl_add_u32 v124, v2, 1, v1
	v_mad_u32_u24 v1, v234, s6, v3
	v_bitop3_b32 v2, v92, v152, 8 bitop3:0x78
	v_lshlrev_b32_e32 v6, 7, v152
	v_lshl_add_u32 v125, v2, 1, v1
	v_bitop3_b32 v2, v92, v157, 32 bitop3:0x36
	v_lshl_add_u32 v126, v2, 1, v1
	v_and_b32_e32 v2, 0x700, v6
	v_lshl_or_b32 v127, s3, 12, v2
	v_or_b32_e32 v2, 16, v234
	v_bitop3_b32 v3, v234, 24, 16 bitop3:0xc8
	v_bitop3_b32 v2, v92, v2, 24 bitop3:0x78
	v_bitop3_b32 v3, v92, v3, 32 bitop3:0x36
	v_add_u32_e32 v5, 0x900, v1
	v_lshlrev_b32_e32 v2, 1, v2
	v_lshlrev_b32_e32 v3, 1, v3
	v_add_u32_e32 v129, v5, v2
	v_add_u32_e32 v130, v5, v3
	v_or_b32_e32 v5, 32, v234
	v_bitop3_b32 v6, v234, 40, 32 bitop3:0xc8
	v_bitop3_b32 v5, v92, v5, 40 bitop3:0x78
	v_bitop3_b32 v6, v92, v6, 32 bitop3:0x36
	v_add_u32_e32 v7, 0x1200, v1
	v_lshlrev_b32_e32 v5, 1, v5
	v_lshlrev_b32_e32 v6, 1, v6
	v_add_u32_e32 v131, v7, v5
	v_add_u32_e32 v132, v7, v6
	v_or_b32_e32 v7, 48, v234
	v_bitop3_b32 v8, v234, 56, 48 bitop3:0xc8
	v_bitop3_b32 v7, v92, v7, 56 bitop3:0x78
	v_bitop3_b32 v8, v92, v8, 32 bitop3:0x36
	v_mul_u32_u24_e32 v0, 0x90, v64
	v_add_u32_e32 v9, 0x1b00, v1
	v_lshlrev_b32_e32 v7, 1, v7
	v_lshlrev_b32_e32 v8, 1, v8
	v_add_u32_e32 v133, v9, v7
	v_add_u32_e32 v134, v9, v8
	v_add_u32_e32 v9, 0x2d00, v1
	v_add_u32_e32 v142, v4, v0
	v_mbcnt_lo_u32_b32 v0, -1, 0
	s_cmp_eq_u32 s3, s2
	v_add_u32_e32 v135, v9, v2
	v_add_u32_e32 v2, 0x3600, v1
	v_add_u32_e32 v1, 0x3f00, v1
	v_mbcnt_hi_u32_b32 v144, -1, v0
	v_bfrev_b32_e32 v0, 0.5
	s_cselect_b64 s[4:5], -1, 0
	v_cmp_eq_u32_e64 s[16:17], 0, v153
	v_cmp_gt_u32_e64 s[18:19], 16, v153
	v_or_b32_e32 v119, 0x200, v64
	v_or_b32_e32 v128, 0x800, v127
	v_add_u32_e32 v136, v9, v3
	v_add_u32_e32 v137, v2, v5
	v_add_u32_e32 v138, v2, v6
	v_add_u32_e32 v139, v1, v7
	v_add_u32_e32 v140, v1, v8
	s_mov_b32 s3, 0xbfb8aa3b
	v_mov_b32_e32 v141, 0x3ecc95a3
	s_mov_b32 s33, 0x3f317218
	s_mov_b32 s43, 0x33800000
	s_mov_b32 s46, 0x3fb8aa3b
	s_mov_b32 s47, 0xc2ce8ed0
	s_mov_b32 s62, 0x42b17218
	s_movk_i32 s63, 0x1600
	s_mov_b32 s64, 0xffff0000
	s_mov_b64 s[6:7], 0x1000
	s_mov_b64 s[38:39], 0x2000
	s_movk_i32 s65, 0x2000
	s_mov_b64 s[40:41], 0x3000
	s_movk_i32 s80, 0x3000
	s_movk_i32 s81, 0x7fff
	s_mov_b32 s42, 0x3db504f3
	v_lshlrev_b32_e32 v66, 1, v64
	v_mov_b32_e32 v143, 0x7f800000
	v_lshl_or_b32 v145, v144, 2, v0
	v_mov_b32_e32 v146, 1
	s_mov_b32 s82, s86
	s_andn2_b64 vcc, exec, s[4:5]
	s_cbranch_vccnz .Lm1pf_skip_0
	s_lshl_b32 s0, s82, 1
	s_ashr_i32 s83, s82, 1
	s_and_b32 s0, s0, 2
	s_add_i32 s44, s0, s2
	s_lshl_b32 s22, s83, 6
	v_or_b32_e32 v186, s22, v153
	v_ashrrev_i32_e32 v187, 31, v186
	v_lshlrev_b64 v[186:187], 5, v[186:187]
	s_ashr_i32 s45, s44, 31
	v_lshl_add_u64 v[186:187], s[54:55], 0, v[186:187]
	v_lshl_add_u64 v[186:187], s[44:45], 2, v[186:187]
	global_load_dword v228, v[186:187], off offset:16
	global_load_dword v229, v[186:187], off
